# weight conversion loop: next tile decoded before the LDS staging ladder, each row group reloaded right after its ds_write
# speedup vs baseline: 1.0093x; 1.0093x over previous
; __device__ __forceinline__ unsigned cvt_pk_bf16(float lo, float hi) { unsigned r; asm volatile("v_cvt_pk_bf16_f32 %0, %1, %2" : "=v"(r) : "v"(lo), "v"(hi)); return r; }
; #define LDS_BARRIER() asm volatile("s_waitcnt lgkmcnt(0)\n\ts_barrier" ::: "memory")
; __device__ void convert_weights(float* tile) {
;     ...
;     for (; t < N_CVT_TILES; t += gridDim.x) {
;         const CvtJob J = cvt_decode(t, pq);
; #pragma unroll
;         for (int ii = 0; ii < 8; ++ii) { float* tp = tile + (ii * 8 + rl) * 257 + c4; tp[0] = cur[ii].x; tp[1] = cur[ii].y; tp[2] = cur[ii].z; tp[3] = cur[ii].w; }
;         const int tn = t + gridDim.x;
;         if (tn < N_CVT_TILES) { const CvtJob Jn = cvt_decode(tn, pq);
; #pragma unroll
;             for (int ii = 0; ii < 8; ++ii) { const f32x4 t_ = __builtin_nontemporal_load((const f32x4*)(Jn.src + (size_t)(Jn.k0 + ii * 8 + rl) * Jn.N + Jn.n0 + c4)); cur[ii] = make_float4(t_[0], t_[1], t_[2], t_[3]); } }
;         LDS_BARRIER();
; #pragma unroll
;         for (int ii = 0; ii < 4; ++ii) { const int f = tid + 512 * ii, n = f >> 3, k8 = (f & 7) * 8; const float* tp = tile + k8 * 257 + n;
;             u32x4 w; w.x = cvt_pk_bf16(tp[0], tp[257]); w.y = cvt_pk_bf16(tp[2 * 257], tp[3 * 257]); w.z = cvt_pk_bf16(tp[4 * 257], tp[5 * 257]); w.w = cvt_pk_bf16(tp[6 * 257], tp[7 * 257]);
;             *(u32x4*)(J.dst + (size_t)(J.n0 + n) * J.K + J.k0 + k8) = w; }
.LBB0_36:
	s_lshr_b32 s16, s39, 8
	s_ff1_i32_b32 s26, s16
	s_add_i32 s16, s16, -1
	s_and_b32 s16, s16, s41
	s_lshr_b32 s26, s41, s26
	s_lshl_b32 s16, s16, 10
	s_and_b32 s26, s26, 0xffff
	s_and_b32 s16, s16, 0x3fffc00
	s_add_u32 s24, s24, s16
	s_addc_u32 s25, s25, 0
	v_lshl_add_u32 v88, s26, 6, v38
	v_mul_u32_u24_e32 v80, s39, v88
	s_lshl_b32 s16, s39, 5
	v_lshl_add_u32 v80, v80, 2, v34
	v_add_u32_e32 v81, s16, v80
	v_add_u32_e32 v82, s16, v81
	v_add_u32_e32 v83, s16, v82
	v_add_u32_e32 v84, s16, v83
	v_add_u32_e32 v85, s16, v84
	v_add_u32_e32 v86, s16, v85
	v_add_u32_e32 v87, s16, v86
	s_waitcnt vmcnt(7)
	ds_write2_b32 v47, v6, v7 offset1:1
	ds_write2_b32 v47, v8, v9 offset0:2 offset1:3
	global_load_dwordx4 v[6:9], v80, s[24:25] nt
	s_waitcnt vmcnt(7)
	ds_write2_b32 v48, v2, v3 offset1:1
	ds_write2_b32 v49, v4, v5 offset1:1
	global_load_dwordx4 v[2:5], v81, s[24:25] nt
	s_waitcnt vmcnt(7)
	ds_write2_b32 v50, v14, v15 offset1:1
	ds_write2_b32 v51, v16, v17 offset1:1
	global_load_dwordx4 v[14:17], v82, s[24:25] nt
	s_waitcnt vmcnt(7)
	ds_write2_b32 v52, v10, v11 offset1:1
	ds_write2_b32 v53, v12, v13 offset1:1
	global_load_dwordx4 v[10:13], v83, s[24:25] nt
	s_waitcnt vmcnt(7)
	ds_write2_b32 v54, v22, v23 offset1:1
	ds_write2_b32 v55, v24, v25 offset1:1
	global_load_dwordx4 v[22:25], v84, s[24:25] nt
	s_waitcnt vmcnt(7)
	ds_write2_b32 v56, v18, v19 offset1:1
	ds_write2_b32 v57, v20, v21 offset1:1
	global_load_dwordx4 v[18:21], v85, s[24:25] nt
	s_waitcnt vmcnt(7)
	ds_write2_b32 v58, v30, v31 offset1:1
	ds_write2_b32 v59, v32, v33 offset1:1
	global_load_dwordx4 v[30:33], v86, s[24:25] nt
	s_waitcnt vmcnt(7)
	ds_write2_b32 v60, v26, v27 offset1:1
	ds_write2_b32 v61, v28, v29 offset1:1
	global_load_dwordx4 v[26:29], v87, s[24:25] nt

; __device__ __forceinline__ CvtJob cvt_decode(int t, const ParamsPtr pq) {
;     t = N_CVT_TILES_K - 1 - t;
;     CvtJob J; const int jj = t / 4352; int r = t % 4352; unsigned char* ws = pq->ws;
;     if (r < 1792) { bf16_t* wp = (bf16_t*)(ws + WS_W + jj * W_POOL_SZ);
;         if (r < 1024) { J.src = pq->in[3] + (size_t)jj * DM * DE2; J.dst = wp + W_POOL_IN / 2; J.K = DM; J.N = DE2; }
;         else if (r < 1280) { r -= 1024; const int g = r >> 6; r &= 63; J.src = pq->in[4] + ((size_t)jj * 4 + g) * 1024 * 1024; J.dst = wp + W_POOL_GRP / 2 + (size_t)g * 1024 * 1024; J.K = 1024; J.N = 1024; }
;         else { r -= 1280; J.src = pq->in[6] + (size_t)jj * DE * DM; J.dst = wp + W_POOL_OUT / 2; J.K = DE; J.N = DM; }
;     } else { r -= 1792; bf16_t* wp = (bf16_t*)(ws + WS_WSSM + jj * W_SSM_SZ);
;         if (r < 1024) { J.src = pq->in[7] + (size_t)jj * DM * DE2; J.dst = wp + W_SSM_IN / 2; J.K = DM; J.N = DE2; }
;         else if (r < 2048) { r -= 1024; J.src = pq->in[16] + (size_t)jj * DE * DE; J.dst = wp + W_SSM_GLU / 2; J.K = DE; J.N = DE; }
;         else { r -= 2048; J.src = pq->in[18] + (size_t)jj * DE * DM; J.dst = wp + W_SSM_OUT / 2; J.K = DE; J.N = DM; }
;     }
;     const int tn = J.N / 256; J.k0 = (r / tn) * 64; J.n0 = (r % tn) * 256; return J;
; __device__ void convert_weights(float* tile) {
;     ...
;     for (; t < N_CVT_TILES; t += gridDim.x) {
;         const CvtJob J = cvt_decode(t, pq);
; #pragma unroll
;         for (int ii = 0; ii < 8; ++ii) { float* tp = tile + (ii * 8 + rl) * 257 + c4; tp[0] = cur[ii].x; tp[1] = cur[ii].y; tp[2] = cur[ii].z; tp[3] = cur[ii].w; }
;         const int tn = t + gridDim.x;
;         if (tn < N_CVT_TILES) { const CvtJob Jn = cvt_decode(tn, pq);
.LBB0_58:
	s_add_i32 s36, s36, s68
	s_cmpk_gt_i32 s36, 0x21ff
	s_cselect_b64 s[22:23], -1, 0
	s_and_b64 vcc, exec, s[22:23]
	s_cbranch_vccnz .Lcv_ladder_plain
	s_add_i32 s24, s34, s35
	s_mul_hi_u32 s16, s24, 0xf0f0f0f1
	s_lshr_b32 s16, s16, 12
	s_mul_i32 s25, s16, 0x1100
	s_sub_i32 s40, s24, s25
	s_cmpk_gt_u32 s40, 0x6ff
	s_mov_b64 s[26:27], -1
	s_cbranch_scc0 .LBB0_69
	s_cmpk_gt_u32 s40, 0xaff
	s_cbranch_scc0 .LBB0_66
	s_cmpk_gt_u32 s40, 0xeff
	s_cbranch_scc0 .LBB0_63
	s_load_dwordx2 s[24:25], s[14:15], 0x90
	s_add_i32 s41, s40, 0xfffff100
	s_lshl_b64 s[26:27], s[16:17], 25
	s_waitcnt lgkmcnt(0)
	s_add_u32 s24, s24, s26
	s_addc_u32 s25, s25, s27
	s_mov_b64 s[26:27], 0

; __device__ void convert_weights(float* tile) {
;     ...
;         for (int ii = 0; ii < 8; ++ii) { float* tp = tile + (ii * 8 + rl) * 257 + c4; tp[0] = cur[ii].x; tp[1] = cur[ii].y; tp[2] = cur[ii].z; tp[3] = cur[ii].w; }
.Lcv_ladder_plain:
	s_waitcnt vmcnt(7)
	ds_write2_b32 v47, v6, v7 offset1:1
	ds_write2_b32 v47, v8, v9 offset0:2 offset1:3
	s_waitcnt vmcnt(6)
	ds_write2_b32 v48, v2, v3 offset1:1
	ds_write2_b32 v49, v4, v5 offset1:1
	s_waitcnt vmcnt(5)
	ds_write2_b32 v50, v14, v15 offset1:1
	ds_write2_b32 v51, v16, v17 offset1:1
	s_waitcnt vmcnt(4)
	ds_write2_b32 v52, v10, v11 offset1:1
	ds_write2_b32 v53, v12, v13 offset1:1
	s_waitcnt vmcnt(3)
	ds_write2_b32 v54, v22, v23 offset1:1
	ds_write2_b32 v55, v24, v25 offset1:1
	s_waitcnt vmcnt(2)
	ds_write2_b32 v56, v18, v19 offset1:1
	ds_write2_b32 v57, v20, v21 offset1:1
	s_waitcnt vmcnt(1)
	ds_write2_b32 v58, v30, v31 offset1:1
	ds_write2_b32 v59, v32, v33 offset1:1
	s_waitcnt vmcnt(0)
	ds_write2_b32 v60, v26, v27 offset1:1
	ds_write2_b32 v61, v28, v29 offset1:1
	s_branch .LBB0_37
